# seams: the first workgroup of each XCD to arrive starts an L2 write-back immediately
# speedup vs baseline: 1.0027x; 1.0027x over previous
.LBB0_212:
	s_or_b64 exec, exec, s[54:55]
	v_cvt_f32_u32_e32 v4, v2
	s_waitcnt vmcnt(0)
	v_readfirstlane_b32 s3, v3
	v_sub_u32_e32 v3, 0, v2
	v_rcp_iflag_f32_e32 v4, v4
	v_add_u32_e32 v5, s3, v1
	v_mul_f32_e32 v4, 0x4f7ffffe, v4
	v_cvt_u32_f32_e32 v4, v4
	v_mul_lo_u32 v1, v3, v4
	v_mul_hi_u32 v1, v4, v1
	v_add_u32_e32 v1, v4, v1
	v_mul_hi_u32 v1, v5, v1
	v_mul_lo_u32 v3, v1, v2
	v_sub_u32_e32 v3, v5, v3
	v_add_u32_e32 v4, 1, v1
	v_cmp_ge_u32_e32 vcc, v3, v2
	s_nop 1
	v_cndmask_b32_e32 v1, v1, v4, vcc
	v_sub_u32_e32 v4, v3, v2
	v_cndmask_b32_e32 v3, v3, v4, vcc
	v_add_u32_e32 v4, 1, v1
	v_cmp_ge_u32_e32 vcc, v3, v2
	v_add_u32_e32 v3, 1, v5
	s_nop 0
	v_cndmask_b32_e32 v1, v1, v4, vcc
	v_mul_lo_u32 v4, v2, v1
	v_add_u32_e32 v2, v4, v2
	v_cmp_ne_u32_e32 vcc, v5, v4
	s_cbranch_vccnz .Lfw_0
	buffer_wbl2 sc1
.Lfw_0:
	v_cmp_ne_u32_e32 vcc, v3, v2
	s_and_saveexec_b64 s[14:15], vcc
	s_xor_b64 s[66:67], exec, s[14:15]
	s_cbranch_execz .LBB0_226
	s_waitcnt lgkmcnt(0)
	v_mov_b32_e32 v0, 0x2000
	global_load_dword v0, v0, s[8:9] offset:1024 sc1
	s_add_u32 s56, s8, 0x2400
	s_addc_u32 s57, s9, 0
	s_waitcnt vmcnt(0)
	v_cmp_eq_u32_e32 vcc, v0, v1
	s_and_saveexec_b64 s[52:53], vcc
	s_cbranch_execz .LBB0_225
	s_add_u32 s54, s30, 0x4200
	s_addc_u32 s55, s31, 0
	s_mov_b32 s3, 1
	s_mov_b64 s[58:59], 0
	v_mov_b32_e32 v0, 0
	s_branch .LBB0_216

.Lfw_1:
	v_cmp_ne_u32_e32 vcc, v3, v2
	s_and_saveexec_b64 s[14:15], vcc
	s_xor_b64 s[66:67], exec, s[14:15]
	s_cbranch_execz .LBB0_389
	s_waitcnt lgkmcnt(0)
	v_mov_b32_e32 v0, 0x2000
	global_load_dword v0, v0, s[10:11] offset:1024 sc1
	s_add_u32 s56, s10, 0x2400
	s_addc_u32 s57, s11, 0
	s_waitcnt vmcnt(0)
	v_cmp_eq_u32_e32 vcc, v0, v1
	s_and_saveexec_b64 s[52:53], vcc
	s_cbranch_execz .LBB0_388
	s_add_u32 s54, s30, 0x4200
	s_addc_u32 s55, s31, 0
	s_mov_b32 s3, 1
	s_mov_b64 s[58:59], 0
	v_mov_b32_e32 v0, 0
	s_branch .LBB0_379

.LBB0_545:
	s_or_b64 exec, exec, s[52:53]
	v_cvt_f32_u32_e32 v4, v2
	s_waitcnt vmcnt(0)
	v_readfirstlane_b32 s3, v3
	v_sub_u32_e32 v3, 0, v2
	v_rcp_iflag_f32_e32 v4, v4
	v_add_u32_e32 v5, s3, v1
	v_mul_f32_e32 v4, 0x4f7ffffe, v4
	v_cvt_u32_f32_e32 v4, v4
	v_mul_lo_u32 v1, v3, v4
	v_mul_hi_u32 v1, v4, v1
	v_add_u32_e32 v1, v4, v1
	v_mul_hi_u32 v1, v5, v1
	v_mul_lo_u32 v3, v1, v2
	v_sub_u32_e32 v3, v5, v3
	v_add_u32_e32 v4, 1, v1
	v_cmp_ge_u32_e32 vcc, v3, v2
	s_nop 1
	v_cndmask_b32_e32 v1, v1, v4, vcc
	v_sub_u32_e32 v4, v3, v2
	v_cndmask_b32_e32 v3, v3, v4, vcc
	v_add_u32_e32 v4, 1, v1
	v_cmp_ge_u32_e32 vcc, v3, v2
	v_add_u32_e32 v3, 1, v5
	s_nop 0
	v_cndmask_b32_e32 v1, v1, v4, vcc
	v_mul_lo_u32 v4, v2, v1
	v_add_u32_e32 v2, v4, v2
	v_cmp_ne_u32_e32 vcc, v5, v4
	s_cbranch_vccnz .Lfw_2
	buffer_wbl2 sc1
.Lfw_2:
	v_cmp_ne_u32_e32 vcc, v3, v2
	s_and_saveexec_b64 s[14:15], vcc
	s_xor_b64 s[42:43], exec, s[14:15]
	s_cbranch_execz .LBB0_559
	s_waitcnt lgkmcnt(0)
	v_mov_b32_e32 v0, 0x2000
	global_load_dword v0, v0, s[10:11] offset:1024 sc1
	s_add_u32 s56, s10, 0x2400
	s_addc_u32 s57, s11, 0
	s_waitcnt vmcnt(0)
	v_cmp_eq_u32_e32 vcc, v0, v1
	s_and_saveexec_b64 s[52:53], vcc
	s_cbranch_execz .LBB0_558
	s_add_u32 s54, s30, 0x4200
	s_addc_u32 s55, s31, 0
	s_mov_b32 s3, 1
	s_mov_b64 s[58:59], 0
	v_mov_b32_e32 v0, 0
	s_branch .LBB0_549

.LBB0_721:
	s_or_b64 exec, exec, s[44:45]
	v_cvt_f32_u32_e32 v4, v2
	s_waitcnt vmcnt(0)
	v_readfirstlane_b32 s3, v3
	v_sub_u32_e32 v3, 0, v2
	v_rcp_iflag_f32_e32 v4, v4
	v_add_u32_e32 v5, s3, v1
	v_mul_f32_e32 v4, 0x4f7ffffe, v4
	v_cvt_u32_f32_e32 v4, v4
	v_mul_lo_u32 v1, v3, v4
	v_mul_hi_u32 v1, v4, v1
	v_add_u32_e32 v1, v4, v1
	v_mul_hi_u32 v1, v5, v1
	v_mul_lo_u32 v3, v1, v2
	v_sub_u32_e32 v3, v5, v3
	v_add_u32_e32 v4, 1, v1
	v_cmp_ge_u32_e32 vcc, v3, v2
	s_nop 1
	v_cndmask_b32_e32 v1, v1, v4, vcc
	v_sub_u32_e32 v4, v3, v2
	v_cndmask_b32_e32 v3, v3, v4, vcc
	v_add_u32_e32 v4, 1, v1
	v_cmp_ge_u32_e32 vcc, v3, v2
	v_add_u32_e32 v3, 1, v5
	s_nop 0
	v_cndmask_b32_e32 v1, v1, v4, vcc
	v_mul_lo_u32 v4, v2, v1
	v_add_u32_e32 v2, v4, v2
	v_cmp_ne_u32_e32 vcc, v5, v4
	s_cbranch_vccnz .Lfw_3
	buffer_wbl2 sc1
.Lfw_3:
	v_cmp_ne_u32_e32 vcc, v3, v2
	s_and_saveexec_b64 s[10:11], vcc
	s_xor_b64 s[10:11], exec, s[10:11]
	s_cbranch_execz .LBB0_735
	s_waitcnt lgkmcnt(0)
	v_mov_b32_e32 v0, 0x2000
	global_load_dword v0, v0, s[8:9] offset:1024 sc1
	s_add_u32 s48, s8, 0x2400
	s_addc_u32 s49, s9, 0
	s_waitcnt vmcnt(0)
	v_cmp_eq_u32_e32 vcc, v0, v1
	s_and_saveexec_b64 s[44:45], vcc
	s_cbranch_execz .LBB0_734
	s_add_u32 s46, s30, 0x4200
	s_addc_u32 s47, s31, 0
	s_mov_b32 s3, 1
	s_mov_b64 s[52:53], 0
	v_mov_b32_e32 v0, 0
	s_branch .LBB0_725

.Lfw_4:
	v_cmp_ne_u32_e32 vcc, v3, v2
	s_and_saveexec_b64 s[10:11], vcc
	s_xor_b64 s[10:11], exec, s[10:11]
	s_cbranch_execz .LBB0_951
	s_waitcnt lgkmcnt(0)
	v_mov_b32_e32 v0, 0x2000
	global_load_dword v0, v0, s[8:9] offset:1024 sc1
	s_add_u32 s48, s8, 0x2400
	s_addc_u32 s49, s9, 0
	s_waitcnt vmcnt(0)
	v_cmp_eq_u32_e32 vcc, v0, v1
	s_and_saveexec_b64 s[44:45], vcc
	s_cbranch_execz .LBB0_950
	s_add_u32 s46, s30, 0x4200
	s_addc_u32 s47, s31, 0
	s_mov_b32 s3, 1
	s_mov_b64 s[50:51], 0
	v_mov_b32_e32 v0, 0
	s_branch .LBB0_941

.Lfw_6:
	v_cmp_ne_u32_e32 vcc, v3, v2
	s_and_saveexec_b64 s[10:11], vcc
	s_xor_b64 s[10:11], exec, s[10:11]
	s_cbranch_execz .LBB0_1253
	s_waitcnt lgkmcnt(0)
	v_mov_b32_e32 v0, 0x2000
	global_load_dword v0, v0, s[6:7] offset:1024 sc1
	s_add_u32 s48, s6, 0x2400
	s_addc_u32 s49, s7, 0
	s_waitcnt vmcnt(0)
	v_cmp_eq_u32_e32 vcc, v0, v1
	s_and_saveexec_b64 s[44:45], vcc
	s_cbranch_execz .LBB0_1252
	s_add_u32 s46, s30, 0x4200
	s_addc_u32 s47, s31, 0
	s_mov_b32 s3, 1
	s_mov_b64 s[50:51], 0
	v_mov_b32_e32 v0, 0
	s_branch .LBB0_1243

.LBB0_2140:
	s_or_b64 exec, exec, s[42:43]
	v_cvt_f32_u32_e32 v4, v2
	s_waitcnt vmcnt(0)
	v_readfirstlane_b32 s3, v3
	v_sub_u32_e32 v3, 0, v2
	v_rcp_iflag_f32_e32 v4, v4
	v_add_u32_e32 v5, s3, v1
	v_mul_f32_e32 v4, 0x4f7ffffe, v4
	v_cvt_u32_f32_e32 v4, v4
	v_mul_lo_u32 v1, v3, v4
	v_mul_hi_u32 v1, v4, v1
	v_add_u32_e32 v1, v4, v1
	v_mul_hi_u32 v1, v5, v1
	v_mul_lo_u32 v3, v1, v2
	v_sub_u32_e32 v3, v5, v3
	v_add_u32_e32 v4, 1, v1
	v_cmp_ge_u32_e32 vcc, v3, v2
	s_nop 1
	v_cndmask_b32_e32 v1, v1, v4, vcc
	v_sub_u32_e32 v4, v3, v2
	v_cndmask_b32_e32 v3, v3, v4, vcc
	v_add_u32_e32 v4, 1, v1
	v_cmp_ge_u32_e32 vcc, v3, v2
	v_add_u32_e32 v3, 1, v5
	s_nop 0
	v_cndmask_b32_e32 v1, v1, v4, vcc
	v_mul_lo_u32 v4, v2, v1
	v_add_u32_e32 v2, v4, v2
	v_cmp_ne_u32_e32 vcc, v5, v4
	s_cbranch_vccnz .Lfw_12
	buffer_wbl2 sc1
.Lfw_12:
	v_cmp_ne_u32_e32 vcc, v3, v2
	s_and_saveexec_b64 s[10:11], vcc
	s_xor_b64 s[10:11], exec, s[10:11]
	s_cbranch_execz .LBB0_2154
	s_waitcnt lgkmcnt(0)
	v_mov_b32_e32 v0, 0x2000
	global_load_dword v0, v0, s[8:9] offset:1024 sc1
	s_add_u32 s46, s8, 0x2400
	s_addc_u32 s47, s9, 0
	s_waitcnt vmcnt(0)
	v_cmp_eq_u32_e32 vcc, v0, v1
	s_and_saveexec_b64 s[42:43], vcc
	s_cbranch_execz .LBB0_2153
	s_add_u32 s44, s30, 0x4200
	s_addc_u32 s45, s31, 0
	s_mov_b32 s3, 1
	s_mov_b64 s[48:49], 0
	v_mov_b32_e32 v0, 0
	s_branch .LBB0_2144

.LBB0_2283:
	s_or_b64 exec, exec, s[10:11]
	v_cvt_f32_u32_e32 v4, v2
	s_waitcnt vmcnt(0)
	v_readfirstlane_b32 s3, v3
	v_sub_u32_e32 v3, 0, v2
	v_rcp_iflag_f32_e32 v4, v4
	v_add_u32_e32 v5, s3, v1
	v_mul_f32_e32 v4, 0x4f7ffffe, v4
	v_cvt_u32_f32_e32 v4, v4
	v_mul_lo_u32 v1, v3, v4
	v_mul_hi_u32 v1, v4, v1
	v_add_u32_e32 v1, v4, v1
	v_mul_hi_u32 v1, v5, v1
	v_mul_lo_u32 v3, v1, v2
	v_sub_u32_e32 v3, v5, v3
	v_add_u32_e32 v4, 1, v1
	v_cmp_ge_u32_e32 vcc, v3, v2
	s_nop 1
	v_cndmask_b32_e32 v1, v1, v4, vcc
	v_sub_u32_e32 v4, v3, v2
	v_cndmask_b32_e32 v3, v3, v4, vcc
	v_add_u32_e32 v4, 1, v1
	v_cmp_ge_u32_e32 vcc, v3, v2
	v_add_u32_e32 v3, 1, v5
	s_nop 0
	v_cndmask_b32_e32 v1, v1, v4, vcc
	v_mul_lo_u32 v4, v2, v1
	v_add_u32_e32 v2, v4, v2
	v_cmp_ne_u32_e32 vcc, v5, v4
	s_cbranch_vccnz .Lfw_13
	buffer_wbl2 sc1
.Lfw_13:
	v_cmp_ne_u32_e32 vcc, v3, v2
	s_and_saveexec_b64 s[6:7], vcc
	s_xor_b64 s[6:7], exec, s[6:7]
	s_cbranch_execz .LBB0_2297
	s_waitcnt lgkmcnt(0)
	v_mov_b32_e32 v0, 0x2000
	global_load_dword v0, v0, s[0:1] offset:1024 sc1
	s_add_u32 s16, s0, 0x2400
	s_addc_u32 s17, s1, 0
	s_waitcnt vmcnt(0)
	v_cmp_eq_u32_e32 vcc, v0, v1
	s_and_saveexec_b64 s[10:11], vcc
	s_cbranch_execz .LBB0_2296
	s_add_u32 s14, s30, 0x4200
	s_addc_u32 s15, s31, 0
	s_mov_b32 s3, 1
	s_mov_b64 s[18:19], 0
	v_mov_b32_e32 v0, 0
	s_branch .LBB0_2287
